# grid barrier: non-leader WGs poll the top-level generation word directly (drops the per-XCD release hop)
# baseline (speedup 1.0000x reference)
.LBB0_564:
	s_or_b64 exec, exec, s[14:15]
	v_cvt_f32_u32_e32 v4, v2
	s_waitcnt vmcnt(0)
	v_readfirstlane_b32 s4, v3
	v_sub_u32_e32 v3, 0, v2
	v_rcp_iflag_f32_e32 v4, v4
	v_add_u32_e32 v5, s4, v1
	v_mul_f32_e32 v4, 0x4f7ffffe, v4
	v_cvt_u32_f32_e32 v4, v4
	v_mul_lo_u32 v1, v3, v4
	v_mul_hi_u32 v1, v4, v1
	v_add_u32_e32 v1, v4, v1
	v_mul_hi_u32 v1, v5, v1
	v_mul_lo_u32 v3, v1, v2
	v_sub_u32_e32 v3, v5, v3
	v_add_u32_e32 v4, 1, v1
	v_cmp_ge_u32_e32 vcc, v3, v2
	s_nop 1
	v_cndmask_b32_e32 v1, v1, v4, vcc
	v_sub_u32_e32 v4, v3, v2
	v_cndmask_b32_e32 v3, v3, v4, vcc
	v_add_u32_e32 v4, 1, v1
	v_cmp_ge_u32_e32 vcc, v3, v2
	v_add_u32_e32 v3, 1, v5
	s_nop 0
	v_cndmask_b32_e32 v1, v1, v4, vcc
	v_mul_lo_u32 v4, v2, v1
	v_add_u32_e32 v2, v4, v2
	v_cmp_ne_u32_e32 vcc, v3, v2
	s_and_saveexec_b64 s[4:5], vcc
	s_xor_b64 s[4:5], exec, s[4:5]
	s_cbranch_execz .LBB0_578
	s_waitcnt lgkmcnt(0)
	s_add_u32 s18, s90, 0x23500
	s_addc_u32 s19, s91, 0
	global_load_dword v0, v209, s[18:19] sc1
	s_waitcnt vmcnt(0)
	v_cmp_eq_u32_e32 vcc, v0, v1
	s_and_saveexec_b64 s[14:15], vcc
	s_cbranch_execz .LBB0_577
	s_add_u32 s16, s90, 0x20200
	s_addc_u32 s17, s91, 0
	s_mov_b32 s6, 1
	s_mov_b64 s[30:31], 0
	s_branch .LBB0_568

.LBB0_595:
	s_or_b64 exec, exec, s[4:5]
	s_mov_b64 s[4:5], exec
	v_mbcnt_lo_u32_b32 v0, s4, 0
	v_mbcnt_hi_u32_b32 v0, s5, v0
	v_cmp_eq_u32_e32 vcc, 0, v0
	s_waitcnt vmcnt(0)
	buffer_inv sc1
	s_and_saveexec_b64 s[14:15], vcc
	s_cbranch_execz .LBB0_10
	s_bcnt1_i32_b64 s4, s[4:5]
	v_mov_b32_e32 v0, s4
	s_branch .LBB0_10
